# s23 + prep_wt: P1 deferred weight-prep stores written through (less dirty L2 for barrier 1's write-back)
# speedup vs baseline: 1.0029x; 1.0029x over previous
.LBB0_192:
	s_cmpk_gt_i32 s8, 0xff
	s_mov_b64 s[0:1], -1
	s_cbranch_scc0 .LBB0_216
	s_cmpk_gt_u32 s8, 0x1ff
	s_cbranch_scc0 .LBB0_213
	s_cmpk_gt_u32 s8, 0x3ff
	s_cbranch_scc0 .LBB0_210
	s_cmpk_gt_u32 s8, 0xbff
	s_cbranch_scc0 .LBB0_197
	s_add_i32 s0, s8, 0xf400
	s_bfe_u32 s1, s0, 0xb0005
	s_and_b32 s0, s10, 0x3e0
	s_lshl_b32 s4, s0, 2
	v_lshl_add_u64 v[0:1], v[34:35], 0, s[4:5]
	v_lshl_or_b32 v32, s1, 18, v60
	v_lshl_add_u64 v[28:29], v[0:1], 0, v[32:33]
	v_add_co_u32_e32 v4, vcc, 0x8000, v28
	v_or_b32_e32 v32, s0, v55
	s_nop 0
	v_addc_co_u32_e32 v5, vcc, 0, v29, vcc
	v_add_co_u32_e32 v8, vcc, 0x10000, v28
	global_load_dwordx4 v[0:3], v[28:29], off nt
	s_nop 0
	global_load_dwordx4 v[4:7], v[4:5], off nt
	v_addc_co_u32_e32 v9, vcc, 0, v29, vcc
	v_add_co_u32_e32 v12, vcc, 0x18000, v28
	s_lshl_b32 s4, s1, 17
	s_nop 0
	v_addc_co_u32_e32 v13, vcc, 0, v29, vcc
	v_add_co_u32_e32 v16, vcc, 0x20000, v28
	global_load_dwordx4 v[8:11], v[8:9], off nt
	s_nop 0
	global_load_dwordx4 v[12:15], v[12:13], off nt
	v_addc_co_u32_e32 v17, vcc, 0, v29, vcc
	v_add_co_u32_e32 v20, vcc, 0x28000, v28
	v_lshl_add_u64 v[78:79], v[36:37], 0, s[4:5]
	s_nop 0
	v_addc_co_u32_e32 v21, vcc, 0, v29, vcc
	global_load_dwordx4 v[16:19], v[16:17], off nt
	s_nop 0
	global_load_dwordx4 v[20:23], v[20:21], off nt
	v_add_co_u32_e32 v24, vcc, 0x30000, v28
	v_lshlrev_b32_e32 v32, 7, v32
	s_nop 0
	v_addc_co_u32_e32 v25, vcc, 0, v29, vcc
	global_load_dwordx4 v[24:27], v[24:25], off nt
	v_add_co_u32_e32 v28, vcc, 0x38000, v28
	s_nop 1
	v_addc_co_u32_e32 v29, vcc, 0, v29, vcc
	global_load_dwordx4 v[28:31], v[28:29], off nt
	s_waitcnt vmcnt(0)
	ds_write2_b32 v61, v0, v1 offset1:1
	ds_write2_b32 v61, v2, v3 offset0:2 offset1:3
	ds_write2_b32 v62, v4, v5 offset1:1
	ds_write2_b32 v63, v6, v7 offset1:1
	ds_write2_b32 v64, v8, v9 offset1:1
	ds_write2_b32 v65, v10, v11 offset1:1
	ds_write2_b32 v66, v12, v13 offset1:1
	ds_write2_b32 v67, v14, v15 offset1:1
	ds_write2_b32 v68, v16, v17 offset1:1
	ds_write2_b32 v69, v18, v19 offset1:1
	ds_write2_b32 v70, v20, v21 offset1:1
	ds_write2_b32 v71, v22, v23 offset1:1
	ds_write2_b32 v72, v24, v25 offset1:1
	ds_write2_b32 v73, v26, v27 offset1:1
	ds_write2_b32 v74, v28, v29 offset1:1
	ds_write2_b32 v75, v30, v31 offset1:1
	s_waitcnt lgkmcnt(0)
	ds_read2_b32 v[4:5], v59 offset0:33 offset1:41
	ds_read2_b32 v[6:7], v59 offset1:8
	ds_read2_b32 v[8:9], v59 offset0:66 offset1:74
	ds_read2_b32 v[10:11], v59 offset0:99 offset1:107
	ds_read2_b32 v[12:13], v59 offset0:132 offset1:140
	ds_read2_b32 v[14:15], v59 offset0:165 offset1:173
	ds_read2_b32 v[16:17], v59 offset0:198 offset1:206
	ds_read2_b32 v[18:19], v59 offset0:231 offset1:239
	s_waitcnt lgkmcnt(6)
	v_bfe_u32 v0, v6, 16, 1
	v_bfe_u32 v1, v4, 16, 1
	s_waitcnt lgkmcnt(5)
	v_bfe_u32 v2, v8, 16, 1
	s_waitcnt lgkmcnt(3)
	v_bfe_u32 v20, v12, 16, 1
	s_waitcnt lgkmcnt(1)
	v_bfe_u32 v22, v16, 16, 1
	v_bfe_u32 v3, v10, 16, 1
	v_bfe_u32 v21, v14, 16, 1
	s_waitcnt lgkmcnt(0)
	v_bfe_u32 v23, v18, 16, 1
	v_add3_u32 v0, v6, v0, s15
	v_add3_u32 v1, v4, v1, s15
	v_add3_u32 v2, v8, v2, s15
	v_add3_u32 v4, v12, v20, s15
	v_add3_u32 v8, v16, v22, s15
	v_add3_u32 v3, v10, v3, s15
	v_add3_u32 v6, v14, v21, s15
	v_add3_u32 v10, v18, v23, s15
	v_lshrrev_b32_e32 v0, 16, v0
	v_lshrrev_b32_e32 v2, 16, v2
	v_lshrrev_b32_e32 v4, 16, v4
	v_lshrrev_b32_e32 v8, 16, v8
	v_and_or_b32 v0, v1, s16, v0
	v_and_or_b32 v1, v3, s16, v2
	v_and_or_b32 v2, v6, s16, v4
	v_and_or_b32 v3, v10, s16, v8
	v_lshl_add_u64 v[20:21], v[78:79], 0, v[32:33]
	global_store_dwordx4 v[20:21], v[0:3], off sc1
	v_bfe_u32 v4, v19, 16, 1
	v_or_b32_e32 v6, s0, v56
	v_bfe_u32 v0, v7, 16, 1
	v_add3_u32 v0, v7, v0, s15
	v_bfe_u32 v1, v5, 16, 1
	v_lshrrev_b32_e32 v0, 16, v0
	v_add3_u32 v1, v5, v1, s15
	v_and_or_b32 v0, v1, s16, v0
	v_bfe_u32 v1, v9, 16, 1
	v_add3_u32 v1, v9, v1, s15
	v_bfe_u32 v2, v11, 16, 1
	v_lshrrev_b32_e32 v1, 16, v1
	v_add3_u32 v2, v11, v2, s15
	v_and_or_b32 v1, v2, s16, v1
	v_bfe_u32 v2, v13, 16, 1
	v_add3_u32 v2, v13, v2, s15
	v_bfe_u32 v3, v15, 16, 1
	v_lshrrev_b32_e32 v2, 16, v2
	v_add3_u32 v3, v15, v3, s15
	v_and_or_b32 v2, v3, s16, v2
	v_bfe_u32 v3, v17, 16, 1
	v_add3_u32 v3, v17, v3, s15
	v_lshrrev_b32_e32 v3, 16, v3
	v_add3_u32 v4, v19, v4, s15
	v_lshlrev_b32_e32 v32, 7, v6
	v_and_or_b32 v3, v4, s16, v3
	ds_read2_b32 v[4:5], v59 offset0:16 offset1:24
	v_lshl_add_u64 v[6:7], v[78:79], 0, v[32:33]
	global_store_dwordx4 v[6:7], v[0:3], off sc1
	ds_read2_b32 v[6:7], v59 offset0:49 offset1:57
	ds_read2_b32 v[8:9], v59 offset0:82 offset1:90
	ds_read2_b32 v[10:11], v59 offset0:115 offset1:123
	s_waitcnt lgkmcnt(3)
	v_bfe_u32 v0, v4, 16, 1
	v_add3_u32 v0, v4, v0, s15
	s_waitcnt lgkmcnt(2)
	v_bfe_u32 v1, v6, 16, 1
	ds_read2_b32 v[12:13], v59 offset0:148 offset1:156
	v_lshrrev_b32_e32 v0, 16, v0
	v_add3_u32 v1, v6, v1, s15
	ds_read2_b32 v[14:15], v59 offset0:181 offset1:189
	v_and_or_b32 v0, v1, s16, v0
	s_waitcnt lgkmcnt(3)
	v_bfe_u32 v1, v8, 16, 1
	v_add3_u32 v1, v8, v1, s15
	s_waitcnt lgkmcnt(2)
	v_bfe_u32 v2, v10, 16, 1
	ds_read2_b32 v[16:17], v59 offset0:214 offset1:222
	v_lshrrev_b32_e32 v1, 16, v1
	v_add3_u32 v2, v10, v2, s15
	ds_read2_b32 v[18:19], v59 offset0:247 offset1:255
	v_and_or_b32 v1, v2, s16, v1
	s_waitcnt lgkmcnt(3)
	v_bfe_u32 v2, v12, 16, 1
	v_add3_u32 v2, v12, v2, s15
	s_waitcnt lgkmcnt(2)
	v_bfe_u32 v3, v14, 16, 1
	v_lshrrev_b32_e32 v2, 16, v2
	v_add3_u32 v3, v14, v3, s15
	v_and_or_b32 v2, v3, s16, v2
	s_waitcnt lgkmcnt(1)
	v_bfe_u32 v3, v16, 16, 1
	v_add3_u32 v3, v16, v3, s15
	s_waitcnt lgkmcnt(0)
	v_bfe_u32 v4, v18, 16, 1
	v_lshrrev_b32_e32 v3, 16, v3
	v_add3_u32 v4, v18, v4, s15
	v_and_or_b32 v3, v4, s16, v3
	v_or_b32_e32 v4, s0, v57
	v_lshlrev_b32_e32 v32, 7, v4
	v_lshl_add_u64 v[20:21], v[78:79], 0, v[32:33]
	global_store_dwordx4 v[20:21], v[0:3], off sc1
	v_bfe_u32 v4, v17, 16, 1
	v_add3_u32 v4, v17, v4, s15
	v_or_b32_e32 v0, s0, v58
	v_bfe_u32 v1, v5, 16, 1
	v_lshlrev_b32_e32 v32, 7, v0
	v_bfe_u32 v0, v7, 16, 1
	v_add3_u32 v1, v5, v1, s15
	v_add3_u32 v0, v7, v0, s15
	v_lshrrev_b32_e32 v1, 16, v1
	v_bfe_u32 v2, v9, 16, 1
	v_and_or_b32 v0, v0, s16, v1
	v_bfe_u32 v1, v11, 16, 1
	v_add3_u32 v2, v9, v2, s15
	v_add3_u32 v1, v11, v1, s15
	v_lshrrev_b32_e32 v2, 16, v2
	v_bfe_u32 v3, v13, 16, 1
	v_and_or_b32 v1, v1, s16, v2
	v_bfe_u32 v2, v15, 16, 1
	v_add3_u32 v3, v13, v3, s15
	v_add3_u32 v2, v15, v2, s15
	v_lshrrev_b32_e32 v3, 16, v3
	v_and_or_b32 v2, v2, s16, v3
	v_bfe_u32 v3, v19, 16, 1
	v_add3_u32 v3, v19, v3, s15
	v_lshrrev_b32_e32 v4, 16, v4
	v_lshl_add_u64 v[20:21], v[78:79], 0, v[32:33]
	v_and_or_b32 v3, v3, s16, v4
	global_store_dwordx4 v[20:21], v[0:3], off sc1
	s_waitcnt lgkmcnt(0)
	s_mov_b64 s[0:1], 0

.LBB0_208:
	v_add_u32_e32 v9, 0x840, v76
	ds_write2_b32 v9, v4, v5 offset1:1
	v_add_u32_e32 v4, 0x848, v76
	ds_write2_b32 v4, v6, v7 offset1:1
	s_waitcnt vmcnt(0)
	v_pk_mul_f32 v[0:1], v[0:1], v[8:9] op_sel_hi:[1,0]
	v_add_u32_e32 v4, 0xc60, v76
	ds_write2_b32 v4, v0, v1 offset1:1
	v_pk_mul_f32 v[0:1], v[2:3], v[8:9] op_sel_hi:[1,0]
	v_add_u32_e32 v2, 0xc68, v76
	ds_write2_b32 v2, v0, v1 offset1:1
	s_waitcnt lgkmcnt(0)
	ds_read2_b32 v[4:5], v59 offset1:8
	ds_read2_b32 v[8:9], v59 offset0:33 offset1:41
	ds_read2_b32 v[10:11], v59 offset0:66 offset1:74
	ds_read2_b32 v[12:13], v59 offset0:99 offset1:107
	ds_read2_b32 v[14:15], v59 offset0:132 offset1:140
	s_waitcnt lgkmcnt(4)
	v_bfe_u32 v0, v4, 16, 1
	v_add3_u32 v0, v4, v0, s15
	s_waitcnt lgkmcnt(3)
	v_bfe_u32 v1, v8, 16, 1
	v_lshrrev_b32_e32 v0, 16, v0
	v_add3_u32 v1, v8, v1, s15
	ds_read2_b32 v[16:17], v59 offset0:165 offset1:173
	v_and_or_b32 v0, v1, s16, v0
	s_waitcnt lgkmcnt(3)
	v_bfe_u32 v1, v10, 16, 1
	v_add3_u32 v1, v10, v1, s15
	s_waitcnt lgkmcnt(2)
	v_bfe_u32 v2, v12, 16, 1
	ds_read2_b32 v[18:19], v59 offset0:198 offset1:206
	v_lshrrev_b32_e32 v1, 16, v1
	v_add3_u32 v2, v12, v2, s15
	ds_read2_b32 v[20:21], v59 offset0:231 offset1:239
	v_and_or_b32 v1, v2, s16, v1
	s_waitcnt lgkmcnt(3)
	v_bfe_u32 v2, v14, 16, 1
	v_add3_u32 v2, v14, v2, s15
	s_waitcnt lgkmcnt(2)
	v_bfe_u32 v3, v16, 16, 1
	v_lshrrev_b32_e32 v2, 16, v2
	v_add3_u32 v3, v16, v3, s15
	v_and_or_b32 v2, v3, s16, v2
	s_waitcnt lgkmcnt(1)
	v_bfe_u32 v3, v18, 16, 1
	v_add3_u32 v3, v18, v3, s15
	s_waitcnt lgkmcnt(0)
	v_bfe_u32 v4, v20, 16, 1
	v_lshrrev_b32_e32 v3, 16, v3
	v_add3_u32 v4, v20, v4, s15
	s_lshl_b32 s4, s21, 1
	v_and_or_b32 v3, v4, s16, v3
	v_or_b32_e32 v4, s20, v55
	v_lshl_add_u64 v[6:7], v[40:41], 0, s[4:5]
	v_lshlrev_b32_e32 v32, 11, v4
	v_lshl_add_u64 v[22:23], v[6:7], 0, v[32:33]
	global_store_dwordx4 v[22:23], v[0:3], off sc1
	v_bfe_u32 v4, v21, 16, 1
	v_or_b32_e32 v8, s20, v56
	v_bfe_u32 v0, v5, 16, 1
	v_add3_u32 v0, v5, v0, s15
	v_bfe_u32 v1, v9, 16, 1
	v_lshrrev_b32_e32 v0, 16, v0
	v_add3_u32 v1, v9, v1, s15
	v_and_or_b32 v0, v1, s16, v0
	v_bfe_u32 v1, v11, 16, 1
	v_add3_u32 v1, v11, v1, s15
	v_bfe_u32 v2, v13, 16, 1
	v_lshrrev_b32_e32 v1, 16, v1
	v_add3_u32 v2, v13, v2, s15
	v_and_or_b32 v1, v2, s16, v1
	v_bfe_u32 v2, v15, 16, 1
	v_add3_u32 v2, v15, v2, s15
	v_bfe_u32 v3, v17, 16, 1
	v_lshrrev_b32_e32 v2, 16, v2
	v_add3_u32 v3, v17, v3, s15
	v_and_or_b32 v2, v3, s16, v2
	v_bfe_u32 v3, v19, 16, 1
	v_add3_u32 v3, v19, v3, s15
	v_lshrrev_b32_e32 v3, 16, v3
	v_add3_u32 v4, v21, v4, s15
	v_lshlrev_b32_e32 v32, 11, v8
	v_and_or_b32 v3, v4, s16, v3
	ds_read2_b32 v[4:5], v59 offset0:16 offset1:24
	v_lshl_add_u64 v[8:9], v[6:7], 0, v[32:33]
	global_store_dwordx4 v[8:9], v[0:3], off sc1
	ds_read2_b32 v[8:9], v59 offset0:49 offset1:57
	ds_read2_b32 v[10:11], v59 offset0:82 offset1:90
	ds_read2_b32 v[12:13], v59 offset0:115 offset1:123
	s_waitcnt lgkmcnt(3)
	v_bfe_u32 v0, v4, 16, 1
	v_add3_u32 v0, v4, v0, s15
	s_waitcnt lgkmcnt(2)
	v_bfe_u32 v1, v8, 16, 1
	ds_read2_b32 v[14:15], v59 offset0:148 offset1:156
	v_lshrrev_b32_e32 v0, 16, v0
	v_add3_u32 v1, v8, v1, s15
	ds_read2_b32 v[16:17], v59 offset0:181 offset1:189
	v_and_or_b32 v0, v1, s16, v0
	s_waitcnt lgkmcnt(3)
	v_bfe_u32 v1, v10, 16, 1
	v_add3_u32 v1, v10, v1, s15
	s_waitcnt lgkmcnt(2)
	v_bfe_u32 v2, v12, 16, 1
	ds_read2_b32 v[18:19], v59 offset0:214 offset1:222
	v_lshrrev_b32_e32 v1, 16, v1
	v_add3_u32 v2, v12, v2, s15
	ds_read2_b32 v[20:21], v59 offset0:247 offset1:255
	v_and_or_b32 v1, v2, s16, v1
	s_waitcnt lgkmcnt(3)
	v_bfe_u32 v2, v14, 16, 1
	v_add3_u32 v2, v14, v2, s15
	s_waitcnt lgkmcnt(2)
	v_bfe_u32 v3, v16, 16, 1
	v_lshrrev_b32_e32 v2, 16, v2
	v_add3_u32 v3, v16, v3, s15
	v_and_or_b32 v2, v3, s16, v2
	s_waitcnt lgkmcnt(1)
	v_bfe_u32 v3, v18, 16, 1
	v_add3_u32 v3, v18, v3, s15
	s_waitcnt lgkmcnt(0)
	v_bfe_u32 v4, v20, 16, 1
	v_lshrrev_b32_e32 v3, 16, v3
	v_add3_u32 v4, v20, v4, s15
	v_and_or_b32 v3, v4, s16, v3
	v_or_b32_e32 v4, s20, v57
	v_lshlrev_b32_e32 v32, 11, v4
	v_lshl_add_u64 v[22:23], v[6:7], 0, v[32:33]
	global_store_dwordx4 v[22:23], v[0:3], off sc1
	v_bfe_u32 v4, v19, 16, 1
	v_add3_u32 v4, v19, v4, s15
	v_or_b32_e32 v0, s20, v58
	v_bfe_u32 v1, v5, 16, 1
	v_lshlrev_b32_e32 v32, 11, v0
	v_bfe_u32 v0, v9, 16, 1
	v_add3_u32 v1, v5, v1, s15
	v_add3_u32 v0, v9, v0, s15
	v_lshrrev_b32_e32 v1, 16, v1
	v_bfe_u32 v2, v11, 16, 1
	v_and_or_b32 v0, v0, s16, v1
	v_bfe_u32 v1, v13, 16, 1
	v_add3_u32 v2, v11, v2, s15
	v_add3_u32 v1, v13, v1, s15
	v_lshrrev_b32_e32 v2, 16, v2
	v_bfe_u32 v3, v15, 16, 1
	v_and_or_b32 v1, v1, s16, v2
	v_bfe_u32 v2, v17, 16, 1
	v_add3_u32 v3, v15, v3, s15
	v_add3_u32 v2, v17, v2, s15
	v_lshrrev_b32_e32 v3, 16, v3
	v_and_or_b32 v2, v2, s16, v3
	v_bfe_u32 v3, v21, 16, 1
	v_add3_u32 v3, v21, v3, s15
	v_lshrrev_b32_e32 v4, 16, v4
	v_lshl_add_u64 v[6:7], v[6:7], 0, v[32:33]
	v_and_or_b32 v3, v3, s16, v4
	global_store_dwordx4 v[6:7], v[0:3], off sc1
	s_waitcnt lgkmcnt(0)

.LBB0_210:
	s_andn2_b64 vcc, exec, s[0:1]
	s_cbranch_vccnz .LBB0_212
	s_add_i32 s0, s12, 0x1fc00
	s_and_b32 s1, s0, 0x1ffc0
	s_and_b32 s0, s10, 0x3e0
	v_or_b32_e32 v2, s1, v55
	s_lshl_b32 s4, s0, 2
	v_lshl_add_u64 v[0:1], v[42:43], 0, s[4:5]
	v_lshlrev_b32_e32 v32, 12, v2
	v_lshl_add_u64 v[28:29], v[0:1], 0, v[32:33]
	v_add_co_u32_e32 v4, vcc, 0x8000, v28
	v_or_b32_e32 v32, s0, v55
	s_nop 0
	v_addc_co_u32_e32 v5, vcc, 0, v29, vcc
	v_add_co_u32_e32 v8, vcc, 0x10000, v28
	global_load_dwordx4 v[0:3], v[28:29], off nt
	s_nop 0
	global_load_dwordx4 v[4:7], v[4:5], off nt
	v_addc_co_u32_e32 v9, vcc, 0, v29, vcc
	v_add_co_u32_e32 v12, vcc, 0x18000, v28
	s_lshl_b32 s4, s1, 1
	s_nop 0
	v_addc_co_u32_e32 v13, vcc, 0, v29, vcc
	v_add_co_u32_e32 v16, vcc, 0x20000, v28
	global_load_dwordx4 v[8:11], v[8:9], off nt
	s_nop 0
	global_load_dwordx4 v[12:15], v[12:13], off nt
	v_addc_co_u32_e32 v17, vcc, 0, v29, vcc
	v_add_co_u32_e32 v20, vcc, 0x28000, v28
	v_lshl_add_u64 v[78:79], v[44:45], 0, s[4:5]
	s_nop 0
	v_addc_co_u32_e32 v21, vcc, 0, v29, vcc
	global_load_dwordx4 v[16:19], v[16:17], off nt
	s_nop 0
	global_load_dwordx4 v[20:23], v[20:21], off nt
	v_add_co_u32_e32 v24, vcc, 0x30000, v28
	v_lshlrev_b32_e32 v32, 11, v32
	s_nop 0
	v_addc_co_u32_e32 v25, vcc, 0, v29, vcc
	global_load_dwordx4 v[24:27], v[24:25], off nt
	v_add_co_u32_e32 v28, vcc, 0x38000, v28
	s_nop 1
	v_addc_co_u32_e32 v29, vcc, 0, v29, vcc
	global_load_dwordx4 v[28:31], v[28:29], off nt
	s_waitcnt vmcnt(0)
	ds_write2_b32 v61, v0, v1 offset1:1
	ds_write2_b32 v61, v2, v3 offset0:2 offset1:3
	ds_write2_b32 v62, v4, v5 offset1:1
	ds_write2_b32 v63, v6, v7 offset1:1
	ds_write2_b32 v64, v8, v9 offset1:1
	ds_write2_b32 v65, v10, v11 offset1:1
	ds_write2_b32 v66, v12, v13 offset1:1
	ds_write2_b32 v67, v14, v15 offset1:1
	ds_write2_b32 v68, v16, v17 offset1:1
	ds_write2_b32 v69, v18, v19 offset1:1
	ds_write2_b32 v70, v20, v21 offset1:1
	ds_write2_b32 v71, v22, v23 offset1:1
	ds_write2_b32 v72, v24, v25 offset1:1
	ds_write2_b32 v73, v26, v27 offset1:1
	ds_write2_b32 v74, v28, v29 offset1:1
	ds_write2_b32 v75, v30, v31 offset1:1
	s_waitcnt lgkmcnt(0)
	ds_read2_b32 v[4:5], v59 offset0:33 offset1:41
	ds_read2_b32 v[6:7], v59 offset1:8
	ds_read2_b32 v[8:9], v59 offset0:66 offset1:74
	ds_read2_b32 v[10:11], v59 offset0:99 offset1:107
	ds_read2_b32 v[12:13], v59 offset0:132 offset1:140
	ds_read2_b32 v[14:15], v59 offset0:165 offset1:173
	ds_read2_b32 v[16:17], v59 offset0:198 offset1:206
	ds_read2_b32 v[18:19], v59 offset0:231 offset1:239
	s_waitcnt lgkmcnt(6)
	v_bfe_u32 v0, v6, 16, 1
	v_bfe_u32 v1, v4, 16, 1
	s_waitcnt lgkmcnt(5)
	v_bfe_u32 v2, v8, 16, 1
	s_waitcnt lgkmcnt(3)
	v_bfe_u32 v20, v12, 16, 1
	s_waitcnt lgkmcnt(1)
	v_bfe_u32 v22, v16, 16, 1
	v_bfe_u32 v3, v10, 16, 1
	v_bfe_u32 v21, v14, 16, 1
	s_waitcnt lgkmcnt(0)
	v_bfe_u32 v23, v18, 16, 1
	v_add3_u32 v0, v6, v0, s15
	v_add3_u32 v1, v4, v1, s15
	v_add3_u32 v2, v8, v2, s15
	v_add3_u32 v4, v12, v20, s15
	v_add3_u32 v8, v16, v22, s15
	v_add3_u32 v3, v10, v3, s15
	v_add3_u32 v6, v14, v21, s15
	v_add3_u32 v10, v18, v23, s15
	v_lshrrev_b32_e32 v0, 16, v0
	v_lshrrev_b32_e32 v2, 16, v2
	v_lshrrev_b32_e32 v4, 16, v4
	v_lshrrev_b32_e32 v8, 16, v8
	v_and_or_b32 v0, v1, s16, v0
	v_and_or_b32 v1, v3, s16, v2
	v_and_or_b32 v2, v6, s16, v4
	v_and_or_b32 v3, v10, s16, v8
	v_lshl_add_u64 v[20:21], v[78:79], 0, v[32:33]
	global_store_dwordx4 v[20:21], v[0:3], off sc1
	v_bfe_u32 v4, v19, 16, 1
	v_or_b32_e32 v6, s0, v56
	v_bfe_u32 v0, v7, 16, 1
	v_add3_u32 v0, v7, v0, s15
	v_bfe_u32 v1, v5, 16, 1
	v_lshrrev_b32_e32 v0, 16, v0
	v_add3_u32 v1, v5, v1, s15
	v_and_or_b32 v0, v1, s16, v0
	v_bfe_u32 v1, v9, 16, 1
	v_add3_u32 v1, v9, v1, s15
	v_bfe_u32 v2, v11, 16, 1
	v_lshrrev_b32_e32 v1, 16, v1
	v_add3_u32 v2, v11, v2, s15
	v_and_or_b32 v1, v2, s16, v1
	v_bfe_u32 v2, v13, 16, 1
	v_add3_u32 v2, v13, v2, s15
	v_bfe_u32 v3, v15, 16, 1
	v_lshrrev_b32_e32 v2, 16, v2
	v_add3_u32 v3, v15, v3, s15
	v_and_or_b32 v2, v3, s16, v2
	v_bfe_u32 v3, v17, 16, 1
	v_add3_u32 v3, v17, v3, s15
	v_lshrrev_b32_e32 v3, 16, v3
	v_add3_u32 v4, v19, v4, s15
	v_lshlrev_b32_e32 v32, 11, v6
	v_and_or_b32 v3, v4, s16, v3
	ds_read2_b32 v[4:5], v59 offset0:16 offset1:24
	v_lshl_add_u64 v[6:7], v[78:79], 0, v[32:33]
	global_store_dwordx4 v[6:7], v[0:3], off sc1
	ds_read2_b32 v[6:7], v59 offset0:49 offset1:57
	ds_read2_b32 v[8:9], v59 offset0:82 offset1:90
	ds_read2_b32 v[10:11], v59 offset0:115 offset1:123
	s_waitcnt lgkmcnt(3)
	v_bfe_u32 v0, v4, 16, 1
	v_add3_u32 v0, v4, v0, s15
	s_waitcnt lgkmcnt(2)
	v_bfe_u32 v1, v6, 16, 1
	ds_read2_b32 v[12:13], v59 offset0:148 offset1:156
	v_lshrrev_b32_e32 v0, 16, v0
	v_add3_u32 v1, v6, v1, s15
	ds_read2_b32 v[14:15], v59 offset0:181 offset1:189
	v_and_or_b32 v0, v1, s16, v0
	s_waitcnt lgkmcnt(3)
	v_bfe_u32 v1, v8, 16, 1
	v_add3_u32 v1, v8, v1, s15
	s_waitcnt lgkmcnt(2)
	v_bfe_u32 v2, v10, 16, 1
	ds_read2_b32 v[16:17], v59 offset0:214 offset1:222
	v_lshrrev_b32_e32 v1, 16, v1
	v_add3_u32 v2, v10, v2, s15
	ds_read2_b32 v[18:19], v59 offset0:247 offset1:255
	v_and_or_b32 v1, v2, s16, v1
	s_waitcnt lgkmcnt(3)
	v_bfe_u32 v2, v12, 16, 1
	v_add3_u32 v2, v12, v2, s15
	s_waitcnt lgkmcnt(2)
	v_bfe_u32 v3, v14, 16, 1
	v_lshrrev_b32_e32 v2, 16, v2
	v_add3_u32 v3, v14, v3, s15
	v_and_or_b32 v2, v3, s16, v2
	s_waitcnt lgkmcnt(1)
	v_bfe_u32 v3, v16, 16, 1
	v_add3_u32 v3, v16, v3, s15
	s_waitcnt lgkmcnt(0)
	v_bfe_u32 v4, v18, 16, 1
	v_lshrrev_b32_e32 v3, 16, v3
	v_add3_u32 v4, v18, v4, s15
	v_and_or_b32 v3, v4, s16, v3
	v_or_b32_e32 v4, s0, v57
	v_lshlrev_b32_e32 v32, 11, v4
	v_lshl_add_u64 v[20:21], v[78:79], 0, v[32:33]
	global_store_dwordx4 v[20:21], v[0:3], off sc1
	v_bfe_u32 v4, v17, 16, 1
	v_add3_u32 v4, v17, v4, s15
	v_or_b32_e32 v0, s0, v58
	v_bfe_u32 v1, v5, 16, 1
	v_lshlrev_b32_e32 v32, 11, v0
	v_bfe_u32 v0, v7, 16, 1
	v_add3_u32 v1, v5, v1, s15
	v_add3_u32 v0, v7, v0, s15
	v_lshrrev_b32_e32 v1, 16, v1
	v_bfe_u32 v2, v9, 16, 1
	v_and_or_b32 v0, v0, s16, v1
	v_bfe_u32 v1, v11, 16, 1
	v_add3_u32 v2, v9, v2, s15
	v_add3_u32 v1, v11, v1, s15
	v_lshrrev_b32_e32 v2, 16, v2
	v_bfe_u32 v3, v13, 16, 1
	v_and_or_b32 v1, v1, s16, v2
	v_bfe_u32 v2, v15, 16, 1
	v_add3_u32 v3, v13, v3, s15
	v_add3_u32 v2, v15, v2, s15
	v_lshrrev_b32_e32 v3, 16, v3
	v_and_or_b32 v2, v2, s16, v3
	v_bfe_u32 v3, v19, 16, 1
	v_add3_u32 v3, v19, v3, s15
	v_lshrrev_b32_e32 v4, 16, v4
	v_lshl_add_u64 v[20:21], v[78:79], 0, v[32:33]
	v_and_or_b32 v3, v3, s16, v4
	global_store_dwordx4 v[20:21], v[0:3], off sc1
	s_waitcnt lgkmcnt(0)

.LBB0_213:
	s_andn2_b64 vcc, exec, s[0:1]
	s_cbranch_vccnz .LBB0_215
	s_and_b32 s1, s12, 0x1c0
	s_and_b32 s0, s10, 0x3e0
	v_or_b32_e32 v2, s1, v55
	s_lshl_b32 s4, s0, 2
	v_lshl_add_u64 v[0:1], v[46:47], 0, s[4:5]
	v_lshlrev_b32_e32 v32, 12, v2
	v_lshl_add_u64 v[28:29], v[0:1], 0, v[32:33]
	v_add_co_u32_e32 v4, vcc, 0x8000, v28
	v_or_b32_e32 v32, s0, v55
	s_nop 0
	v_addc_co_u32_e32 v5, vcc, 0, v29, vcc
	v_add_co_u32_e32 v8, vcc, 0x10000, v28
	global_load_dwordx4 v[0:3], v[28:29], off nt
	s_nop 0
	global_load_dwordx4 v[4:7], v[4:5], off nt
	v_addc_co_u32_e32 v9, vcc, 0, v29, vcc
	v_add_co_u32_e32 v12, vcc, 0x18000, v28
	s_lshl_b32 s4, s1, 1
	s_nop 0
	v_addc_co_u32_e32 v13, vcc, 0, v29, vcc
	v_add_co_u32_e32 v16, vcc, 0x20000, v28
	global_load_dwordx4 v[8:11], v[8:9], off nt
	s_nop 0
	global_load_dwordx4 v[12:15], v[12:13], off nt
	v_addc_co_u32_e32 v17, vcc, 0, v29, vcc
	v_add_co_u32_e32 v20, vcc, 0x28000, v28
	v_lshl_add_u64 v[78:79], v[48:49], 0, s[4:5]
	s_nop 0
	v_addc_co_u32_e32 v21, vcc, 0, v29, vcc
	global_load_dwordx4 v[16:19], v[16:17], off nt
	s_nop 0
	global_load_dwordx4 v[20:23], v[20:21], off nt
	v_add_co_u32_e32 v24, vcc, 0x30000, v28
	v_lshlrev_b32_e32 v32, 12, v32
	s_nop 0
	v_addc_co_u32_e32 v25, vcc, 0, v29, vcc
	global_load_dwordx4 v[24:27], v[24:25], off nt
	v_add_co_u32_e32 v28, vcc, 0x38000, v28
	s_nop 1
	v_addc_co_u32_e32 v29, vcc, 0, v29, vcc
	global_load_dwordx4 v[28:31], v[28:29], off nt
	s_waitcnt vmcnt(0)
	ds_write2_b32 v61, v0, v1 offset1:1
	ds_write2_b32 v61, v2, v3 offset0:2 offset1:3
	ds_write2_b32 v62, v4, v5 offset1:1
	ds_write2_b32 v63, v6, v7 offset1:1
	ds_write2_b32 v64, v8, v9 offset1:1
	ds_write2_b32 v65, v10, v11 offset1:1
	ds_write2_b32 v66, v12, v13 offset1:1
	ds_write2_b32 v67, v14, v15 offset1:1
	ds_write2_b32 v68, v16, v17 offset1:1
	ds_write2_b32 v69, v18, v19 offset1:1
	ds_write2_b32 v70, v20, v21 offset1:1
	ds_write2_b32 v71, v22, v23 offset1:1
	ds_write2_b32 v72, v24, v25 offset1:1
	ds_write2_b32 v73, v26, v27 offset1:1
	ds_write2_b32 v74, v28, v29 offset1:1
	ds_write2_b32 v75, v30, v31 offset1:1
	s_waitcnt lgkmcnt(0)
	ds_read2_b32 v[4:5], v59 offset0:33 offset1:41
	ds_read2_b32 v[6:7], v59 offset1:8
	ds_read2_b32 v[8:9], v59 offset0:66 offset1:74
	ds_read2_b32 v[10:11], v59 offset0:99 offset1:107
	ds_read2_b32 v[12:13], v59 offset0:132 offset1:140
	ds_read2_b32 v[14:15], v59 offset0:165 offset1:173
	ds_read2_b32 v[16:17], v59 offset0:198 offset1:206
	ds_read2_b32 v[18:19], v59 offset0:231 offset1:239
	s_waitcnt lgkmcnt(6)
	v_bfe_u32 v0, v6, 16, 1
	v_bfe_u32 v1, v4, 16, 1
	s_waitcnt lgkmcnt(5)
	v_bfe_u32 v2, v8, 16, 1
	s_waitcnt lgkmcnt(3)
	v_bfe_u32 v20, v12, 16, 1
	s_waitcnt lgkmcnt(1)
	v_bfe_u32 v22, v16, 16, 1
	v_bfe_u32 v3, v10, 16, 1
	v_bfe_u32 v21, v14, 16, 1
	s_waitcnt lgkmcnt(0)
	v_bfe_u32 v23, v18, 16, 1
	v_add3_u32 v0, v6, v0, s15
	v_add3_u32 v1, v4, v1, s15
	v_add3_u32 v2, v8, v2, s15
	v_add3_u32 v4, v12, v20, s15
	v_add3_u32 v8, v16, v22, s15
	v_add3_u32 v3, v10, v3, s15
	v_add3_u32 v6, v14, v21, s15
	v_add3_u32 v10, v18, v23, s15
	v_lshrrev_b32_e32 v0, 16, v0
	v_lshrrev_b32_e32 v2, 16, v2
	v_lshrrev_b32_e32 v4, 16, v4
	v_lshrrev_b32_e32 v8, 16, v8
	v_and_or_b32 v0, v1, s16, v0
	v_and_or_b32 v1, v3, s16, v2
	v_and_or_b32 v2, v6, s16, v4
	v_and_or_b32 v3, v10, s16, v8
	v_lshl_add_u64 v[20:21], v[78:79], 0, v[32:33]
	global_store_dwordx4 v[20:21], v[0:3], off sc1
	v_bfe_u32 v4, v19, 16, 1
	v_or_b32_e32 v6, s0, v56
	v_bfe_u32 v0, v7, 16, 1
	v_add3_u32 v0, v7, v0, s15
	v_bfe_u32 v1, v5, 16, 1
	v_lshrrev_b32_e32 v0, 16, v0
	v_add3_u32 v1, v5, v1, s15
	v_and_or_b32 v0, v1, s16, v0
	v_bfe_u32 v1, v9, 16, 1
	v_add3_u32 v1, v9, v1, s15
	v_bfe_u32 v2, v11, 16, 1
	v_lshrrev_b32_e32 v1, 16, v1
	v_add3_u32 v2, v11, v2, s15
	v_and_or_b32 v1, v2, s16, v1
	v_bfe_u32 v2, v13, 16, 1
	v_add3_u32 v2, v13, v2, s15
	v_bfe_u32 v3, v15, 16, 1
	v_lshrrev_b32_e32 v2, 16, v2
	v_add3_u32 v3, v15, v3, s15
	v_and_or_b32 v2, v3, s16, v2
	v_bfe_u32 v3, v17, 16, 1
	v_add3_u32 v3, v17, v3, s15
	v_lshrrev_b32_e32 v3, 16, v3
	v_add3_u32 v4, v19, v4, s15
	v_lshlrev_b32_e32 v32, 12, v6
	v_and_or_b32 v3, v4, s16, v3
	ds_read2_b32 v[4:5], v59 offset0:16 offset1:24
	v_lshl_add_u64 v[6:7], v[78:79], 0, v[32:33]
	global_store_dwordx4 v[6:7], v[0:3], off sc1
	ds_read2_b32 v[6:7], v59 offset0:49 offset1:57
	ds_read2_b32 v[8:9], v59 offset0:82 offset1:90
	ds_read2_b32 v[10:11], v59 offset0:115 offset1:123
	s_waitcnt lgkmcnt(3)
	v_bfe_u32 v0, v4, 16, 1
	v_add3_u32 v0, v4, v0, s15
	s_waitcnt lgkmcnt(2)
	v_bfe_u32 v1, v6, 16, 1
	ds_read2_b32 v[12:13], v59 offset0:148 offset1:156
	v_lshrrev_b32_e32 v0, 16, v0
	v_add3_u32 v1, v6, v1, s15
	ds_read2_b32 v[14:15], v59 offset0:181 offset1:189
	v_and_or_b32 v0, v1, s16, v0
	s_waitcnt lgkmcnt(3)
	v_bfe_u32 v1, v8, 16, 1
	v_add3_u32 v1, v8, v1, s15
	s_waitcnt lgkmcnt(2)
	v_bfe_u32 v2, v10, 16, 1
	ds_read2_b32 v[16:17], v59 offset0:214 offset1:222
	v_lshrrev_b32_e32 v1, 16, v1
	v_add3_u32 v2, v10, v2, s15
	ds_read2_b32 v[18:19], v59 offset0:247 offset1:255
	v_and_or_b32 v1, v2, s16, v1
	s_waitcnt lgkmcnt(3)
	v_bfe_u32 v2, v12, 16, 1
	v_add3_u32 v2, v12, v2, s15
	s_waitcnt lgkmcnt(2)
	v_bfe_u32 v3, v14, 16, 1
	v_lshrrev_b32_e32 v2, 16, v2
	v_add3_u32 v3, v14, v3, s15
	v_and_or_b32 v2, v3, s16, v2
	s_waitcnt lgkmcnt(1)
	v_bfe_u32 v3, v16, 16, 1
	v_add3_u32 v3, v16, v3, s15
	s_waitcnt lgkmcnt(0)
	v_bfe_u32 v4, v18, 16, 1
	v_lshrrev_b32_e32 v3, 16, v3
	v_add3_u32 v4, v18, v4, s15
	v_and_or_b32 v3, v4, s16, v3
	v_or_b32_e32 v4, s0, v57
	v_lshlrev_b32_e32 v32, 12, v4
	v_lshl_add_u64 v[20:21], v[78:79], 0, v[32:33]
	global_store_dwordx4 v[20:21], v[0:3], off sc1
	v_bfe_u32 v4, v17, 16, 1
	v_add3_u32 v4, v17, v4, s15
	v_or_b32_e32 v0, s0, v58
	v_bfe_u32 v1, v5, 16, 1
	v_lshlrev_b32_e32 v32, 12, v0
	v_bfe_u32 v0, v7, 16, 1
	v_add3_u32 v1, v5, v1, s15
	v_add3_u32 v0, v7, v0, s15
	v_lshrrev_b32_e32 v1, 16, v1
	v_bfe_u32 v2, v9, 16, 1
	v_and_or_b32 v0, v0, s16, v1
	v_bfe_u32 v1, v11, 16, 1
	v_add3_u32 v2, v9, v2, s15
	v_add3_u32 v1, v11, v1, s15
	v_lshrrev_b32_e32 v2, 16, v2
	v_bfe_u32 v3, v13, 16, 1
	v_and_or_b32 v1, v1, s16, v2
	v_bfe_u32 v2, v15, 16, 1
	v_add3_u32 v3, v13, v3, s15
	v_add3_u32 v2, v15, v2, s15
	v_lshrrev_b32_e32 v3, 16, v3
	v_and_or_b32 v2, v2, s16, v3
	v_bfe_u32 v3, v19, 16, 1
	v_add3_u32 v3, v19, v3, s15
	v_lshrrev_b32_e32 v4, 16, v4
	v_lshl_add_u64 v[20:21], v[78:79], 0, v[32:33]
	v_and_or_b32 v3, v3, s16, v4
	global_store_dwordx4 v[20:21], v[0:3], off sc1
	s_waitcnt lgkmcnt(0)

.LBB0_216:
	s_andn2_b64 vcc, exec, s[0:1]
	s_cbranch_vccnz .LBB0_191
	s_ashr_i32 s0, s8, 31
	s_lshr_b32 s0, s0, 27
	s_add_i32 s0, s8, s0
	s_ashr_i32 s0, s0, 5
	s_lshl_b32 s20, s0, 6
	s_lshl_b32 s0, s0, 10
	v_or_b32_e32 v28, s20, v55
	s_sub_i32 s0, s10, s0
	v_or_b32_e32 v2, 8, v28
	v_or_b32_e32 v8, 16, v28
	v_or_b32_e32 v10, 24, v28
	v_or_b32_e32 v16, 32, v28
	v_or_b32_e32 v18, 40, v28
	s_ashr_i32 s1, s0, 31
	v_ashrrev_i32_e32 v29, 31, v28
	v_ashrrev_i32_e32 v3, 31, v2
	v_ashrrev_i32_e32 v9, 31, v8
	v_ashrrev_i32_e32 v11, 31, v10
	v_ashrrev_i32_e32 v17, 31, v16
	v_ashrrev_i32_e32 v19, 31, v18
	v_lshl_add_u64 v[30:31], s[0:1], 2, v[50:51]
	v_lshlrev_b64 v[0:1], 12, v[28:29]
	v_lshlrev_b64 v[2:3], 12, v[2:3]
	v_lshlrev_b64 v[8:9], 12, v[8:9]
	v_lshlrev_b64 v[10:11], 12, v[10:11]
	v_lshlrev_b64 v[16:17], 12, v[16:17]
	v_lshlrev_b64 v[18:19], 12, v[18:19]
	v_lshl_add_u64 v[0:1], v[30:31], 0, v[0:1]
	v_lshl_add_u64 v[4:5], v[30:31], 0, v[2:3]
	v_lshl_add_u64 v[8:9], v[30:31], 0, v[8:9]
	v_lshl_add_u64 v[12:13], v[30:31], 0, v[10:11]
	v_lshl_add_u64 v[16:17], v[30:31], 0, v[16:17]
	v_lshl_add_u64 v[20:21], v[30:31], 0, v[18:19]
	global_load_dwordx4 v[0:3], v[0:1], off nt
	s_nop 0
	global_load_dwordx4 v[4:7], v[4:5], off nt
	s_nop 0
	global_load_dwordx4 v[8:11], v[8:9], off nt
	s_nop 0
	global_load_dwordx4 v[12:15], v[12:13], off nt
	s_nop 0
	global_load_dwordx4 v[16:19], v[16:17], off nt
	s_nop 0
	global_load_dwordx4 v[20:23], v[20:21], off nt
	v_or_b32_e32 v24, 48, v28
	v_ashrrev_i32_e32 v25, 31, v24
	v_lshlrev_b64 v[24:25], 12, v[24:25]
	v_or_b32_e32 v28, 56, v28
	v_lshl_add_u64 v[24:25], v[30:31], 0, v[24:25]
	v_ashrrev_i32_e32 v29, 31, v28
	global_load_dwordx4 v[24:27], v[24:25], off nt
	v_lshlrev_b64 v[28:29], 12, v[28:29]
	v_lshl_add_u64 v[28:29], v[30:31], 0, v[28:29]
	global_load_dwordx4 v[28:31], v[28:29], off nt
	v_add_u32_e32 v80, s0, v55
	s_ashr_i32 s21, s20, 31
	v_ashrrev_i32_e32 v81, 31, v80
	v_lshl_add_u64 v[78:79], s[20:21], 1, v[52:53]
	s_waitcnt vmcnt(0)
	ds_write2_b32 v61, v0, v1 offset1:1
	ds_write2_b32 v61, v2, v3 offset0:2 offset1:3
	ds_write2_b32 v62, v4, v5 offset1:1
	ds_write2_b32 v63, v6, v7 offset1:1
	ds_write2_b32 v64, v8, v9 offset1:1
	ds_write2_b32 v65, v10, v11 offset1:1
	ds_write2_b32 v66, v12, v13 offset1:1
	ds_write2_b32 v67, v14, v15 offset1:1
	ds_write2_b32 v68, v16, v17 offset1:1
	ds_write2_b32 v69, v18, v19 offset1:1
	ds_write2_b32 v70, v20, v21 offset1:1
	ds_write2_b32 v71, v22, v23 offset1:1
	ds_write2_b32 v72, v24, v25 offset1:1
	ds_write2_b32 v73, v26, v27 offset1:1
	ds_write2_b32 v74, v28, v29 offset1:1
	ds_write2_b32 v75, v30, v31 offset1:1
	s_waitcnt lgkmcnt(0)
	ds_read2_b32 v[4:5], v59 offset0:33 offset1:41
	ds_read2_b32 v[6:7], v59 offset1:8
	ds_read2_b32 v[8:9], v59 offset0:66 offset1:74
	ds_read2_b32 v[10:11], v59 offset0:99 offset1:107
	ds_read2_b32 v[12:13], v59 offset0:132 offset1:140
	ds_read2_b32 v[14:15], v59 offset0:165 offset1:173
	ds_read2_b32 v[16:17], v59 offset0:198 offset1:206
	ds_read2_b32 v[18:19], v59 offset0:231 offset1:239
	s_waitcnt lgkmcnt(6)
	v_bfe_u32 v0, v6, 16, 1
	v_bfe_u32 v1, v4, 16, 1
	s_waitcnt lgkmcnt(5)
	v_bfe_u32 v2, v8, 16, 1
	s_waitcnt lgkmcnt(3)
	v_bfe_u32 v20, v12, 16, 1
	s_waitcnt lgkmcnt(1)
	v_bfe_u32 v22, v16, 16, 1
	v_bfe_u32 v3, v10, 16, 1
	v_bfe_u32 v21, v14, 16, 1
	s_waitcnt lgkmcnt(0)
	v_bfe_u32 v23, v18, 16, 1
	v_add3_u32 v0, v6, v0, s15
	v_add3_u32 v1, v4, v1, s15
	v_add3_u32 v2, v8, v2, s15
	v_add3_u32 v4, v12, v20, s15
	v_add3_u32 v8, v16, v22, s15
	v_add3_u32 v3, v10, v3, s15
	v_add3_u32 v6, v14, v21, s15
	v_add3_u32 v10, v18, v23, s15
	v_lshrrev_b32_e32 v0, 16, v0
	v_lshrrev_b32_e32 v2, 16, v2
	v_lshrrev_b32_e32 v4, 16, v4
	v_lshrrev_b32_e32 v8, 16, v8
	v_lshlrev_b64 v[20:21], 12, v[80:81]
	v_and_or_b32 v0, v1, s16, v0
	v_and_or_b32 v1, v3, s16, v2
	v_and_or_b32 v2, v6, s16, v4
	v_and_or_b32 v3, v10, s16, v8
	v_lshl_add_u64 v[20:21], v[78:79], 0, v[20:21]
	global_store_dwordx4 v[20:21], v[0:3], off sc1
	v_bfe_u32 v4, v19, 16, 1
	v_add3_u32 v4, v19, v4, s15
	v_bfe_u32 v0, v7, 16, 1
	v_add3_u32 v0, v7, v0, s15
	v_bfe_u32 v1, v5, 16, 1
	v_lshrrev_b32_e32 v0, 16, v0
	v_add3_u32 v1, v5, v1, s15
	v_and_or_b32 v0, v1, s16, v0
	v_bfe_u32 v1, v9, 16, 1
	v_add3_u32 v1, v9, v1, s15
	v_bfe_u32 v2, v11, 16, 1
	v_lshrrev_b32_e32 v1, 16, v1
	v_add3_u32 v2, v11, v2, s15
	v_and_or_b32 v1, v2, s16, v1
	v_bfe_u32 v2, v13, 16, 1
	v_add3_u32 v2, v13, v2, s15
	v_bfe_u32 v3, v15, 16, 1
	v_lshrrev_b32_e32 v2, 16, v2
	v_add3_u32 v3, v15, v3, s15
	v_and_or_b32 v2, v3, s16, v2
	v_bfe_u32 v3, v17, 16, 1
	v_add3_u32 v3, v17, v3, s15
	v_lshrrev_b32_e32 v3, 16, v3
	v_and_or_b32 v3, v4, s16, v3
	v_add_u32_e32 v4, 8, v80
	v_ashrrev_i32_e32 v5, 31, v4
	v_lshlrev_b64 v[4:5], 12, v[4:5]
	ds_read2_b32 v[6:7], v59 offset0:16 offset1:24
	v_lshl_add_u64 v[4:5], v[78:79], 0, v[4:5]
	global_store_dwordx4 v[4:5], v[0:3], off sc1
	ds_read2_b32 v[4:5], v59 offset0:49 offset1:57
	ds_read2_b32 v[8:9], v59 offset0:82 offset1:90
	ds_read2_b32 v[10:11], v59 offset0:115 offset1:123
	s_waitcnt lgkmcnt(3)
	v_bfe_u32 v0, v6, 16, 1
	v_add3_u32 v0, v6, v0, s15
	s_waitcnt lgkmcnt(2)
	v_bfe_u32 v1, v4, 16, 1
	ds_read2_b32 v[12:13], v59 offset0:148 offset1:156
	v_lshrrev_b32_e32 v0, 16, v0
	v_add3_u32 v1, v4, v1, s15
	ds_read2_b32 v[14:15], v59 offset0:181 offset1:189
	v_and_or_b32 v0, v1, s16, v0
	s_waitcnt lgkmcnt(3)
	v_bfe_u32 v1, v8, 16, 1
	v_add3_u32 v1, v8, v1, s15
	s_waitcnt lgkmcnt(2)
	v_bfe_u32 v2, v10, 16, 1
	ds_read2_b32 v[16:17], v59 offset0:214 offset1:222
	v_lshrrev_b32_e32 v1, 16, v1
	v_add3_u32 v2, v10, v2, s15
	ds_read2_b32 v[18:19], v59 offset0:247 offset1:255
	v_and_or_b32 v1, v2, s16, v1
	s_waitcnt lgkmcnt(3)
	v_bfe_u32 v2, v12, 16, 1
	v_add3_u32 v2, v12, v2, s15
	s_waitcnt lgkmcnt(2)
	v_bfe_u32 v3, v14, 16, 1
	v_lshrrev_b32_e32 v2, 16, v2
	v_add3_u32 v3, v14, v3, s15
	v_and_or_b32 v2, v3, s16, v2
	s_waitcnt lgkmcnt(1)
	v_bfe_u32 v3, v16, 16, 1
	v_add_u32_e32 v20, 16, v80
	v_add3_u32 v3, v16, v3, s15
	s_waitcnt lgkmcnt(0)
	v_bfe_u32 v4, v18, 16, 1
	v_ashrrev_i32_e32 v21, 31, v20
	v_lshrrev_b32_e32 v3, 16, v3
	v_add3_u32 v4, v18, v4, s15
	v_lshlrev_b64 v[20:21], 12, v[20:21]
	v_and_or_b32 v3, v4, s16, v3
	v_lshl_add_u64 v[20:21], v[78:79], 0, v[20:21]
	global_store_dwordx4 v[20:21], v[0:3], off sc1
	v_bfe_u32 v4, v17, 16, 1
	v_add3_u32 v4, v17, v4, s15
	v_add_u32_e32 v0, 24, v80
	v_ashrrev_i32_e32 v1, 31, v0
	v_lshlrev_b64 v[0:1], 12, v[0:1]
	v_lshl_add_u64 v[20:21], v[78:79], 0, v[0:1]
	v_bfe_u32 v1, v7, 16, 1
	v_bfe_u32 v0, v5, 16, 1
	v_add3_u32 v1, v7, v1, s15
	v_add3_u32 v0, v5, v0, s15
	v_lshrrev_b32_e32 v1, 16, v1
	v_bfe_u32 v2, v9, 16, 1
	v_and_or_b32 v0, v0, s16, v1
	v_bfe_u32 v1, v11, 16, 1
	v_add3_u32 v2, v9, v2, s15
	v_add3_u32 v1, v11, v1, s15
	v_lshrrev_b32_e32 v2, 16, v2
	v_bfe_u32 v3, v13, 16, 1
	v_and_or_b32 v1, v1, s16, v2
	v_bfe_u32 v2, v15, 16, 1
	v_add3_u32 v3, v13, v3, s15
	v_add3_u32 v2, v15, v2, s15
	v_lshrrev_b32_e32 v3, 16, v3
	v_and_or_b32 v2, v2, s16, v3
	v_bfe_u32 v3, v19, 16, 1
	v_add3_u32 v3, v19, v3, s15
	v_lshrrev_b32_e32 v4, 16, v4
	v_and_or_b32 v3, v3, s16, v4
	global_store_dwordx4 v[20:21], v[0:3], off sc1
	s_waitcnt lgkmcnt(0)
	s_branch .LBB0_191
